# band attention: K/V LDS tiles double-buffered (address regs XOR-toggled per iteration), first barrier of each tile iteration removed
# baseline (speedup 1.0000x reference)
.LBB0_452:
	s_cmp_ge_i32 s23, s24
	s_cselect_b64 s[26:27], -1, 0
	v_add_u32_e32 v2, v114, v151
	s_and_b64 vcc, exec, s[26:27]
	s_waitcnt lgkmcnt(0)
	s_waitcnt vmcnt(0)
	ds_write_b128 v2, v[102:105]
	ds_write_b128 v164, v[98:101] offset:9216
	s_waitcnt lgkmcnt(0)
	s_barrier
	s_cbranch_vccnz .LBB0_454
	v_ashrrev_i32_e32 v129, 31, v128
	v_lshlrev_b64 v[4:5], 11, v[128:129]
	v_lshl_add_u64 v[6:7], v[126:127], 0, v[4:5]
	v_lshl_add_u64 v[4:5], v[124:125], 0, v[4:5]
	global_load_dwordx4 v[102:105], v[4:5], off
	global_load_dwordx4 v[98:101], v[6:7], off

.LBB0_463:
	v_xor_b32_e32 v114, 0x8000, v114
	v_xor_b32_e32 v164, 0x8000, v164
	v_xor_b32_e32 v165, 0x8000, v165
	v_xor_b32_e32 v153, 0x8000, v153
	s_add_i32 s23, s23, 1
	v_subrev_u32_e32 v119, 64, v119
	s_add_i32 s64, s64, -1
	v_add_u32_e32 v128, 64, v128
	s_and_b64 vcc, exec, s[26:27]
	s_cbranch_vccnz .LBB0_466
	v_mov_b32_e32 v173, v50
	s_branch .LBB0_452
